# attention QK^T: K-fragment ds_reads software-pipelined 8 deep into free VGPRs with counted lgkmcnt (was one exposed LDS round trip per MFMA), on v32
# speedup vs baseline: 1.0063x; 1.0063x over previous
; #define LAS __attribute__((address_space(3)))
; __device__ __forceinline__ void attn_phase(const bf16_t* qkv, bf16_t* opart, float* ml, LAS unsigned char* lds, int wave, int lane, int G) {
;     ...
;         for (int kt = 0; kt < 5; ++kt) {
;             bf16x8 kf[4];
; #pragma unroll
;             for (int ks = 0; ks < 4; ++ks) kf[ks] = *(const LAS bf16x8*)(lds + krd + kt * 32 * AT_KP + ks * 32);
;             f32x16 acc;
; #pragma unroll
;             for (int v = 0; v < 16; ++v) acc[v] = 0.f;
; #pragma unroll
;             for (int ks = 0; ks < 4; ++ks) acc = __builtin_amdgcn_mfma_f32_32x32x16_bf16(kf[ks], q[ks], acc, 0, 0, 0);
;             st[kt] = acc;
;         }
; #pragma unroll
;         for (int v = 0; v < 16; ++v) { const int j = (v & 3) + 8 * (v >> 2) + 4 * hh; if (j < i32) st[0][v] = -1e30f; if (j > i32) st[4][v] = -1e30f; }
;         if (l0 < 128) {
; #pragma unroll
;             for (int kt = 0; kt < 4; ++kt)
; #pragma unroll
;                 for (int v = 0; v < 16; ++v) { const int j = (v & 3) + 8 * (v >> 2) + 4 * hh; if (l0 - 128 + 32 * kt + j < 0) st[kt][v] = -1e30f; }
;         }
.LBB0_699:
	s_add_i32 s13, s73, s77
	s_cmpk_gt_u32 s13, 0x7f
	ds_read_b128 v[212:215], v172
	ds_read_b128 v[216:219], v172 offset:32
	ds_read_b128 v[220:223], v172 offset:64
	ds_read_b128 v[224:227], v172 offset:96
	ds_read_b128 v[232:235], v172 offset:4608
	ds_read_b128 v[236:239], v172 offset:4640
	ds_read_b128 v[240:243], v172 offset:4672
	ds_read_b128 v[244:247], v172 offset:4704
	s_waitcnt lgkmcnt(7)
	v_mfma_f32_32x32x16_bf16 v[64:79], v[212:215], v[48:51], 0
	ds_read_b128 v[212:215], v172 offset:9216
	s_waitcnt lgkmcnt(7)
	v_mfma_f32_32x32x16_bf16 v[64:79], v[216:219], v[152:155], v[64:79]
	ds_read_b128 v[216:219], v172 offset:9248
	s_waitcnt lgkmcnt(7)
	v_mfma_f32_32x32x16_bf16 v[64:79], v[220:223], v[148:151], v[64:79]
	ds_read_b128 v[220:223], v172 offset:9280
	s_waitcnt lgkmcnt(7)
	v_mfma_f32_32x32x16_bf16 v[64:79], v[224:227], v[144:147], v[64:79]
	ds_read_b128 v[224:227], v172 offset:9312
	s_waitcnt lgkmcnt(7)
	v_mfma_f32_32x32x16_bf16 v[32:47], v[232:235], v[48:51], 0
	ds_read_b128 v[232:235], v172 offset:13824
	s_waitcnt lgkmcnt(7)
	v_mfma_f32_32x32x16_bf16 v[32:47], v[236:239], v[152:155], v[32:47]
	ds_read_b128 v[236:239], v172 offset:13856
	s_waitcnt lgkmcnt(7)
	v_mfma_f32_32x32x16_bf16 v[32:47], v[240:243], v[148:151], v[32:47]
	ds_read_b128 v[240:243], v172 offset:13888
	s_waitcnt lgkmcnt(7)
	v_mfma_f32_32x32x16_bf16 v[32:47], v[244:247], v[144:147], v[32:47]
	ds_read_b128 v[244:247], v172 offset:13920
	s_waitcnt lgkmcnt(7)
	v_mfma_f32_32x32x16_bf16 v[16:31], v[212:215], v[48:51], 0
	ds_read_b128 v[212:215], v172 offset:18432
	s_waitcnt lgkmcnt(7)
	v_mfma_f32_32x32x16_bf16 v[16:31], v[216:219], v[152:155], v[16:31]
	ds_read_b128 v[216:219], v172 offset:18464
	s_waitcnt lgkmcnt(7)
	v_mfma_f32_32x32x16_bf16 v[16:31], v[220:223], v[148:151], v[16:31]
	ds_read_b128 v[220:223], v172 offset:18496
	s_waitcnt lgkmcnt(7)
	v_mfma_f32_32x32x16_bf16 v[16:31], v[224:227], v[144:147], v[16:31]
	ds_read_b128 v[224:227], v172 offset:18528
	s_waitcnt lgkmcnt(7)
	v_mfma_f32_32x32x16_bf16 v[0:15], v[232:235], v[48:51], 0
	s_waitcnt lgkmcnt(6)
	v_mfma_f32_32x32x16_bf16 v[0:15], v[236:239], v[152:155], v[0:15]
	s_waitcnt lgkmcnt(5)
	v_mfma_f32_32x32x16_bf16 v[0:15], v[240:243], v[148:151], v[0:15]
	s_waitcnt lgkmcnt(4)
	v_mfma_f32_32x32x16_bf16 v[0:15], v[244:247], v[144:147], v[0:15]
	s_waitcnt lgkmcnt(3)
	v_mfma_f32_32x32x16_bf16 v[48:63], v[212:215], v[48:51], 0
	s_waitcnt lgkmcnt(2)
	v_mfma_f32_32x32x16_bf16 v[48:63], v[216:219], v[152:155], v[48:63]
	s_waitcnt lgkmcnt(1)
	v_mfma_f32_32x32x16_bf16 v[48:63], v[220:223], v[148:151], v[48:63]
	s_waitcnt lgkmcnt(0)
	v_mfma_f32_32x32x16_bf16 v[48:63], v[224:227], v[144:147], v[48:63]
	s_cbranch_scc1 .LBB0_701
	s_cmpk_lt_u32 s13, 0x60
	v_mov_b32_e32 v64, 0xf149f2ca
	s_cselect_b64 vcc, -1, 0
	s_cmp_lt_u32 s13, 64
	v_cndmask_b32_e32 v47, v47, v64, vcc
	v_cndmask_b32_e32 v46, v46, v64, vcc
	v_cndmask_b32_e32 v45, v45, v64, vcc
	v_cndmask_b32_e32 v44, v44, v64, vcc
	v_cndmask_b32_e32 v43, v43, v64, vcc
	v_cndmask_b32_e32 v42, v42, v64, vcc
	v_cndmask_b32_e32 v41, v41, v64, vcc
	v_cndmask_b32_e32 v40, v40, v64, vcc
	v_cndmask_b32_e32 v39, v39, v64, vcc
	v_cndmask_b32_e32 v38, v38, v64, vcc
	v_cndmask_b32_e32 v37, v37, v64, vcc
	v_cndmask_b32_e32 v36, v36, v64, vcc
	v_cndmask_b32_e32 v35, v35, v64, vcc
	v_cndmask_b32_e32 v34, v34, v64, vcc
	v_cndmask_b32_e32 v33, v33, v64, vcc
	v_cndmask_b32_e32 v32, v32, v64, vcc
	s_cselect_b64 vcc, -1, 0
	s_cmp_eq_u32 s13, 0
	v_cndmask_b32_e32 v31, v31, v64, vcc
	v_cndmask_b32_e32 v30, v30, v64, vcc
	v_cndmask_b32_e32 v29, v29, v64, vcc
	v_cndmask_b32_e32 v28, v28, v64, vcc
	v_cndmask_b32_e32 v27, v27, v64, vcc
	v_cndmask_b32_e32 v26, v26, v64, vcc
	v_cndmask_b32_e32 v25, v25, v64, vcc
	v_cndmask_b32_e32 v24, v24, v64, vcc
	v_cndmask_b32_e32 v23, v23, v64, vcc
	v_cndmask_b32_e32 v22, v22, v64, vcc
	v_cndmask_b32_e32 v21, v21, v64, vcc
	v_cndmask_b32_e32 v20, v20, v64, vcc
	v_cndmask_b32_e32 v19, v19, v64, vcc
	v_cndmask_b32_e32 v18, v18, v64, vcc
	v_cndmask_b32_e32 v17, v17, v64, vcc
	v_cndmask_b32_e32 v16, v16, v64, vcc
	s_cselect_b64 vcc, -1, 0
	v_cndmask_b32_e32 v15, v15, v64, vcc
	v_cndmask_b32_e32 v14, v14, v64, vcc
	v_cndmask_b32_e32 v13, v13, v64, vcc
	v_cndmask_b32_e32 v12, v12, v64, vcc
	v_cndmask_b32_e32 v11, v11, v64, vcc
	v_cndmask_b32_e32 v10, v10, v64, vcc
	v_cndmask_b32_e32 v9, v9, v64, vcc
	v_cndmask_b32_e32 v8, v8, v64, vcc
	v_cndmask_b32_e32 v7, v7, v64, vcc
	v_cndmask_b32_e32 v6, v6, v64, vcc
	v_cndmask_b32_e32 v5, v5, v64, vcc
	v_cndmask_b32_e32 v4, v4, v64, vcc
	v_cndmask_b32_e32 v3, v3, v64, vcc
	v_cndmask_b32_e32 v2, v2, v64, vcc
	v_cndmask_b32_e32 v1, v1, v64, vcc
	v_cndmask_b32_e32 v0, v0, v64, vcc
	v_mov_b32_e32 v153, 0xf149f2ca
	v_mov_b32_e32 v151, 0xf149f2ca
	v_mov_b32_e32 v148, 0xf149f2ca
	v_mov_b32_e32 v147, 0xf149f2ca
	v_mov_b32_e32 v146, 0xf149f2ca
	v_mov_b32_e32 v65, 0xf149f2ca
	v_mov_b32_e32 v68, 0xf149f2ca
	v_mov_b32_e32 v144, 0xf149f2ca
	v_mov_b32_e32 v73, 0xf149f2ca
	v_mov_b32_e32 v72, 0xf149f2ca
	v_mov_b32_e32 v71, 0xf149f2ca
	v_mov_b32_e32 v70, 0xf149f2ca
	v_mov_b32_e32 v67, 0xf149f2ca
	v_mov_b32_e32 v69, 0xf149f2ca
	v_mov_b32_e32 v66, 0xf149f2ca
	s_branch .LBB0_702
